# phase 0: LoRA transposition loads hoisted to the start of the phase (ahead of the w_in tile loop), convert/store after it
# speedup vs baseline: 1.0019x; 1.0019x over previous
.LBB0_8:
	s_or_b64 exec, exec, s[6:7]
	s_cmpk_gt_i32 s2, 0x47f
	s_cbranch_scc1 .LBB0_41
	s_waitcnt lgkmcnt(0)
	s_lshr_b32 s16, s2, 1
	s_and_b32 s17, s2, 1
	s_lshl_b32 s17, s17, 9
	v_add_u32_e32 v1, s17, v0
	v_lshlrev_b32_e32 v2, 2, v1
	s_cmp_lt_u32 s16, 96
	s_cbranch_scc0 .Llri_a0
	s_lshl_b32 s18, s16, 12
	s_add_u32 s20, s46, s18
	s_addc_u32 s21, s47, 0
	s_branch .Llri_j1

.Llri_j1:
	s_cmp_lt_u32 s16, 64
	s_cbranch_scc0 .Llri_g1
	s_add_u32 s19, s16, 32
	s_lshl_b32 s18, s19, 12
	s_add_u32 s24, s50, s18
	s_addc_u32 s25, s51, 0
	s_branch .Llri_j2

.Llri_j2:
	s_add_u32 s19, s16, 64
	s_lshl_b32 s18, s19, 12
	s_add_u32 s28, s52, s18
	s_addc_u32 s29, s53, 0
	global_load_dword v244, v2, s[20:21]
	global_load_dword v245, v2, s[24:25]
	global_load_dword v246, v2, s[28:29]
	s_cmp_lt_u32 s16, 64
	s_cbranch_scc0 .Llri_no3
	s_add_u32 s19, s16, 0xc0
	s_lshl_b32 s18, s19, 12
	s_add_u32 s12, s52, s18
	s_addc_u32 s13, s53, 0
	global_load_dword v247, v2, s[12:13]
.Llri_no3:
	v_and_b32_e32 v1, 15, v0
	v_lshlrev_b32_e32 v2, 4, v1
	v_lshrrev_b32_e32 v3, 4, v0
	v_mul_u32_u24_e32 v4, 0x104, v3
	v_add_u32_e32 v20, v4, v2
	v_add_u32_e32 v21, 0x2080, v20
	v_add_u32_e32 v22, 0x2080, v21
	v_add_u32_e32 v23, 0x2080, v22
	v_add_u32_e32 v24, 0x2080, v23
	v_add_u32_e32 v25, 0x2080, v24
	v_add_u32_e32 v26, 0x2080, v25
	v_add_u32_e32 v27, 0x2080, v26
	v_and_b32_e32 v5, 7, v0
	v_lshlrev_b32_e32 v5, 3, v5
	v_lshrrev_b32_e32 v6, 3, v0
	v_mul_u32_u24_e32 v7, 0x104, v5
	v_lshl_add_u32 v7, v6, 2, v7
	v_lshlrev_b32_e32 v28, 2, v3
	v_lshlrev_b32_e32 v31, 1, v5
	v_lshlrev_b32_e32 v29, 12, v6
	v_add_u32_e32 v29, v29, v31
	s_mov_b32 s6, s2
	s_mul_i32 s7, s6, 0x1c72
	s_lshr_b32 s7, s7, 20
	s_mul_i32 s10, s7, 0x90
	s_sub_u32 s10, s6, s10
	s_mov_b32 s76, 0
	s_lshl_b32 s29, s10, 6
	s_cmp_lt_u32 s10, 55
	s_cbranch_scc1 .Lt0_ns_p0
	s_sub_u32 s29, s29, 64
	s_cmp_eq_u32 s10, 55
	s_cselect_b32 s76, 1, 0

.LBB0_41:
	v_lshl_or_b32 v1, s2, 9, v0
	s_mov_b32 s6, 0x70000
	v_cmp_gt_i32_e32 vcc, s6, v1
	s_and_saveexec_b64 s[6:7], vcc
	s_cbranch_execz .LBB0_52
	s_waitcnt lgkmcnt(0)
	s_lshr_b32 s16, s2, 1
	s_and_b32 s17, s2, 1
	s_lshl_b32 s17, s17, 9
	v_add_u32_e32 v1, s17, v0
	v_mul_u32_u24_e32 v3, 0xc0, v1
	v_lshlrev_b32_e32 v4, 9, v1
	s_cmp_lt_u32 s16, 96
	s_cbranch_scc0 .Llrf_a0
	s_lshl_b32 s18, s16, 1
	s_add_u32 s18, s18, 0x7600000
	s_add_u32 s22, s70, s18
	s_addc_u32 s23, s71, 0
	v_mov_b32_e32 v10, v3
	s_branch .Llrf_j1
.Llrf_a0:
	s_sub_u32 s19, s16, 96
	s_lshl_b32 s18, s19, 1
	s_add_u32 s18, s18, 0x7630000
	s_add_u32 s22, s70, s18
	s_addc_u32 s23, s71, 0
	v_mov_b32_e32 v10, v3
.Llrf_j1:
	s_cmp_lt_u32 s16, 64
	s_cbranch_scc0 .Llrf_g1
	s_add_u32 s19, s16, 32
	s_lshl_b32 s18, s19, 1
	s_add_u32 s18, s18, 0x7630000
	s_add_u32 s26, s70, s18
	s_addc_u32 s27, s71, 0
	v_mov_b32_e32 v11, v3
	s_branch .Llrf_j2
.Llrf_g1:
	s_sub_u32 s19, s16, 64
	s_lshl_b32 s18, s19, 1
	s_add_u32 s18, s18, 0x7660000
	s_add_u32 s26, s70, s18
	s_addc_u32 s27, s71, 0
	v_mov_b32_e32 v11, v4
.Llrf_j2:
	s_add_u32 s19, s16, 64
	s_lshl_b32 s18, s19, 1
	s_add_u32 s18, s18, 0x7660000
	s_add_u32 s30, s70, s18
	s_addc_u32 s31, s71, 0
	v_mov_b32_e32 v12, v4
	s_waitcnt vmcnt(0)
	v_cvt_pk_bf16_f32 v5, v244, v244
	global_store_short v10, v5, s[22:23]
	v_cvt_pk_bf16_f32 v6, v245, v245
	global_store_short v11, v6, s[26:27]
	v_cvt_pk_bf16_f32 v7, v246, v246
	global_store_short v12, v7, s[30:31]
	s_cmp_lt_u32 s16, 64
	s_cbranch_scc0 .Llrf_done
	s_add_u32 s19, s16, 0xc0
	s_lshl_b32 s18, s19, 1
	s_add_u32 s18, s18, 0x7660000
	s_add_u32 s14, s70, s18
	s_addc_u32 s15, s71, 0
	v_cvt_pk_bf16_f32 v8, v247, v247
	global_store_short v4, v8, s[14:15]
